# s5_scan carry loop: the 32 s_end loads of a 16-chunk trip issued together instead of one chunk ahead
# speedup vs baseline: 1.0067x; 1.0044x over previous
; DEVI int otid() { int t = threadIdx.x; asm volatile("" : "+v"(t)); return t; }
; DEVI int obid() { int t = blockIdx.x; asm volatile("" : "+s"(t)); return t; }
; DEVI u16 f2bf(float f) { return (u16)(cvt_pk(f, 0.f) & 0xffffu); }
; DEVI void s5_scan(const Params& p) {
;     const float* apow = (const float*)(p.ws + OFF_APOW); const float* send = (const float*)(p.ws + OFF_SEND); u16* ue = (u16*)(p.ws + OFF_UEXT);
;     for (int e = obid() * 512 + otid(); e < 64 * 4 * 64; e += gridDim.x * 512) { const int pp = e & 63, b = (e >> 6) & 3, g = e >> 8;
;         const float ar = apow[(((size_t)g * 64 + pp) * 34 + 32) * 2], ai = apow[(((size_t)g * 64 + pp) * 34 + 32) * 2 + 1]; float rr = 0.f, ri = 0.f;
; #pragma unroll 16
;         for (int c = 0; c < 256; ++c) { const size_t row = (size_t)g * 1024 + b * 256 + c; const float er = send[row * 128 + pp], ei = send[row * 128 + 64 + pp];
;             ue[row * 640 + 512 + pp] = f2bf(rr); ue[row * 640 + 576 + pp] = f2bf(ri);
;             const float nr = ar * rr - ai * ri + er, ni = ar * ri + ai * rr + ei; rr = nr; ri = ni; } }
.LBB0_1185:
	s_waitcnt vmcnt(24)
	v_lshl_add_u64 v[20:21], s[20:21], 0, v[14:15]
	v_lshl_add_u64 v[18:19], s[20:21], 0, v[12:13]
	v_add_co_u32_e32 v22, vcc, 0x12380000, v20
	s_nop 1
	v_addc_co_u32_e32 v23, vcc, 0, v21, vcc
	s_mov_b32 s0, 0x12381000
	v_add_co_u32_e32 v20, vcc, s0, v20
	s_nop 1
	v_addc_co_u32_e32 v21, vcc, 0, v21, vcc
	global_load_dword v60, v[22:23], off
	global_load_dword v61, v[22:23], off offset:256
	global_load_dword v62, v[22:23], off offset:512
	global_load_dword v63, v[22:23], off offset:768
	global_load_dword v64, v[22:23], off offset:1024
	global_load_dword v65, v[22:23], off offset:1280
	global_load_dword v66, v[22:23], off offset:1536
	global_load_dword v67, v[22:23], off offset:1792
	global_load_dword v68, v[22:23], off offset:2048
	global_load_dword v69, v[22:23], off offset:2304
	global_load_dword v70, v[22:23], off offset:2560
	global_load_dword v71, v[22:23], off offset:2816
	global_load_dword v72, v[22:23], off offset:3072
	global_load_dword v73, v[22:23], off offset:3328
	global_load_dword v74, v[22:23], off offset:3584
	global_load_dword v75, v[22:23], off offset:3840
	global_load_dword v126, v[20:21], off
	global_load_dword v127, v[20:21], off offset:256
	global_load_dword v128, v[20:21], off offset:512
	global_load_dword v129, v[20:21], off offset:768
	global_load_dword v130, v[20:21], off offset:1024
	global_load_dword v131, v[20:21], off offset:1280
	global_load_dword v132, v[20:21], off offset:1536
	global_load_dword v133, v[20:21], off offset:1792
	global_load_dword v134, v[20:21], off offset:2048
	global_load_dword v135, v[20:21], off offset:2304
	global_load_dword v136, v[20:21], off offset:2560
	global_load_dword v137, v[20:21], off offset:2816
	global_load_dword v138, v[20:21], off offset:3072
	global_load_dword v139, v[20:21], off offset:3328
	global_load_dword v140, v[20:21], off offset:3584
	global_load_dword v141, v[20:21], off offset:3840
	s_mov_b32 s0, 0xd380000
	v_add_co_u32_e32 v142, vcc, s0, v18
	s_nop 1
	v_addc_co_u32_e32 v143, vcc, 0, v19, vcc
	s_mov_b32 s0, 0xd381000
	v_add_co_u32_e32 v144, vcc, s0, v18
	s_nop 1
	v_addc_co_u32_e32 v145, vcc, 0, v19, vcc
	s_mov_b32 s0, 0xd382000
	v_add_co_u32_e32 v146, vcc, s0, v18
	s_nop 1
	v_addc_co_u32_e32 v147, vcc, 0, v19, vcc
	s_mov_b32 s0, 0xd383000
	v_add_co_u32_e32 v148, vcc, s0, v18
	s_nop 1
	v_addc_co_u32_e32 v149, vcc, 0, v19, vcc
	s_mov_b32 s0, 0xd384000
	v_add_co_u32_e32 v150, vcc, s0, v18
	s_nop 1
	v_addc_co_u32_e32 v151, vcc, 0, v19, vcc
	s_add_i32 s6, s6, -16
	v_lshl_add_u64 v[14:15], v[14:15], 0, s[74:75]
	s_mov_b64 s[0:1], 0x5000
	v_lshl_add_u64 v[12:13], v[12:13], 0, s[0:1]
	v_cvt_pk_bf16_f32 v5, v16, s0
	v_pk_mul_f32 v[28:29], v[10:11], v[16:17] op_sel:[0,1]
	global_store_short v[142:143], v5, off offset:1024
	v_cvt_pk_bf16_f32 v5, v17, s0
	v_pk_fma_f32 v[30:31], v[6:7], v[16:17], v[28:29] neg_lo:[0,0,1] neg_hi:[0,0,1]
	v_pk_fma_f32 v[16:17], v[6:7], v[16:17], v[28:29] op_sel_hi:[1,0,1]
	global_store_short v[142:143], v5, off offset:1152
	v_mov_b32_e32 v31, v17
	s_waitcnt vmcnt(32)
	v_pk_add_f32 v[16:17], v[30:31], v[60:61]
	s_nop 0
	v_cvt_pk_bf16_f32 v5, v16, s0
	v_pk_mul_f32 v[28:29], v[10:11], v[16:17] op_sel:[0,1]
	global_store_short v[142:143], v5, off offset:2304
	v_cvt_pk_bf16_f32 v5, v17, s0
	v_pk_fma_f32 v[30:31], v[6:7], v[16:17], v[28:29] neg_lo:[0,0,1] neg_hi:[0,0,1]
	v_pk_fma_f32 v[16:17], v[6:7], v[16:17], v[28:29] op_sel_hi:[1,0,1]
	global_store_short v[142:143], v5, off offset:2432
	v_mov_b32_e32 v31, v17
	s_waitcnt vmcnt(32)
	v_pk_add_f32 v[16:17], v[30:31], v[62:63]
	s_nop 0
	v_cvt_pk_bf16_f32 v5, v16, s0
	v_pk_mul_f32 v[28:29], v[10:11], v[16:17] op_sel:[0,1]
	global_store_short v[142:143], v5, off offset:3584
	v_cvt_pk_bf16_f32 v5, v17, s0
	v_pk_fma_f32 v[30:31], v[6:7], v[16:17], v[28:29] neg_lo:[0,0,1] neg_hi:[0,0,1]
	v_pk_fma_f32 v[16:17], v[6:7], v[16:17], v[28:29] op_sel_hi:[1,0,1]
	global_store_short v[142:143], v5, off offset:3712
	v_mov_b32_e32 v31, v17
	s_waitcnt vmcnt(32)
	v_pk_add_f32 v[16:17], v[30:31], v[64:65]
	s_nop 0
	v_cvt_pk_bf16_f32 v5, v16, s0
	v_pk_mul_f32 v[28:29], v[10:11], v[16:17] op_sel:[0,1]
	global_store_short v[144:145], v5, off offset:768
	v_cvt_pk_bf16_f32 v5, v17, s0
	v_pk_fma_f32 v[30:31], v[6:7], v[16:17], v[28:29] neg_lo:[0,0,1] neg_hi:[0,0,1]
	v_pk_fma_f32 v[16:17], v[6:7], v[16:17], v[28:29] op_sel_hi:[1,0,1]
	global_store_short v[144:145], v5, off offset:896
	v_mov_b32_e32 v31, v17
	s_waitcnt vmcnt(32)
	v_pk_add_f32 v[16:17], v[30:31], v[66:67]
	s_nop 0
	v_cvt_pk_bf16_f32 v5, v16, s0
	v_pk_mul_f32 v[28:29], v[10:11], v[16:17] op_sel:[0,1]
	global_store_short v[144:145], v5, off offset:2048
	v_cvt_pk_bf16_f32 v5, v17, s0
	v_pk_fma_f32 v[30:31], v[6:7], v[16:17], v[28:29] neg_lo:[0,0,1] neg_hi:[0,0,1]
	v_pk_fma_f32 v[16:17], v[6:7], v[16:17], v[28:29] op_sel_hi:[1,0,1]
	global_store_short v[144:145], v5, off offset:2176
	v_mov_b32_e32 v31, v17
	s_waitcnt vmcnt(32)
	v_pk_add_f32 v[16:17], v[30:31], v[68:69]
	s_nop 0
	v_cvt_pk_bf16_f32 v5, v16, s0
	v_pk_mul_f32 v[28:29], v[10:11], v[16:17] op_sel:[0,1]
	global_store_short v[144:145], v5, off offset:3328
	v_cvt_pk_bf16_f32 v5, v17, s0
	v_pk_fma_f32 v[30:31], v[6:7], v[16:17], v[28:29] neg_lo:[0,0,1] neg_hi:[0,0,1]
	v_pk_fma_f32 v[16:17], v[6:7], v[16:17], v[28:29] op_sel_hi:[1,0,1]
	global_store_short v[144:145], v5, off offset:3456
	v_mov_b32_e32 v31, v17
	s_waitcnt vmcnt(32)
; DEVI int otid() { int t = threadIdx.x; asm volatile("" : "+v"(t)); return t; }
; DEVI int obid() { int t = blockIdx.x; asm volatile("" : "+s"(t)); return t; }
; DEVI u16 f2bf(float f) { return (u16)(cvt_pk(f, 0.f) & 0xffffu); }
; DEVI void s5_scan(const Params& p) {
;     const float* apow = (const float*)(p.ws + OFF_APOW); const float* send = (const float*)(p.ws + OFF_SEND); u16* ue = (u16*)(p.ws + OFF_UEXT);
;     for (int e = obid() * 512 + otid(); e < 64 * 4 * 64; e += gridDim.x * 512) { const int pp = e & 63, b = (e >> 6) & 3, g = e >> 8;
;         const float ar = apow[(((size_t)g * 64 + pp) * 34 + 32) * 2], ai = apow[(((size_t)g * 64 + pp) * 34 + 32) * 2 + 1]; float rr = 0.f, ri = 0.f;
; #pragma unroll 16
;         for (int c = 0; c < 256; ++c) { const size_t row = (size_t)g * 1024 + b * 256 + c; const float er = send[row * 128 + pp], ei = send[row * 128 + 64 + pp];
;             ue[row * 640 + 512 + pp] = f2bf(rr); ue[row * 640 + 576 + pp] = f2bf(ri);
;             const float nr = ar * rr - ai * ri + er, ni = ar * ri + ai * rr + ei; rr = nr; ri = ni; } }
	v_pk_add_f32 v[16:17], v[30:31], v[70:71]
	s_nop 0
	v_cvt_pk_bf16_f32 v5, v16, s0
	v_pk_mul_f32 v[28:29], v[10:11], v[16:17] op_sel:[0,1]
	global_store_short v[146:147], v5, off offset:512
	v_cvt_pk_bf16_f32 v5, v17, s0
	v_pk_fma_f32 v[30:31], v[6:7], v[16:17], v[28:29] neg_lo:[0,0,1] neg_hi:[0,0,1]
	v_pk_fma_f32 v[16:17], v[6:7], v[16:17], v[28:29] op_sel_hi:[1,0,1]
	global_store_short v[146:147], v5, off offset:640
	v_mov_b32_e32 v31, v17
	s_waitcnt vmcnt(32)
	v_pk_add_f32 v[16:17], v[30:31], v[72:73]
	s_nop 0
	v_cvt_pk_bf16_f32 v5, v16, s0
	v_pk_mul_f32 v[28:29], v[10:11], v[16:17] op_sel:[0,1]
	global_store_short v[146:147], v5, off offset:1792
	v_cvt_pk_bf16_f32 v5, v17, s0
	v_pk_fma_f32 v[30:31], v[6:7], v[16:17], v[28:29] neg_lo:[0,0,1] neg_hi:[0,0,1]
	v_pk_fma_f32 v[16:17], v[6:7], v[16:17], v[28:29] op_sel_hi:[1,0,1]
	global_store_short v[146:147], v5, off offset:1920
	v_mov_b32_e32 v31, v17
	s_waitcnt vmcnt(32)
	v_pk_add_f32 v[16:17], v[30:31], v[74:75]
	s_nop 0
	v_cvt_pk_bf16_f32 v5, v16, s0
	v_pk_mul_f32 v[28:29], v[10:11], v[16:17] op_sel:[0,1]
	global_store_short v[146:147], v5, off offset:3072
	v_cvt_pk_bf16_f32 v5, v17, s0
	v_pk_fma_f32 v[30:31], v[6:7], v[16:17], v[28:29] neg_lo:[0,0,1] neg_hi:[0,0,1]
	v_pk_fma_f32 v[16:17], v[6:7], v[16:17], v[28:29] op_sel_hi:[1,0,1]
	global_store_short v[146:147], v5, off offset:3200
	v_mov_b32_e32 v31, v17
	s_waitcnt vmcnt(32)
	v_pk_add_f32 v[16:17], v[30:31], v[126:127]
	s_nop 0
	v_cvt_pk_bf16_f32 v5, v16, s0
	v_pk_mul_f32 v[28:29], v[10:11], v[16:17] op_sel:[0,1]
	global_store_short v[148:149], v5, off offset:256
	v_cvt_pk_bf16_f32 v5, v17, s0
	v_pk_fma_f32 v[30:31], v[6:7], v[16:17], v[28:29] neg_lo:[0,0,1] neg_hi:[0,0,1]
	v_pk_fma_f32 v[16:17], v[6:7], v[16:17], v[28:29] op_sel_hi:[1,0,1]
	global_store_short v[148:149], v5, off offset:384
	v_mov_b32_e32 v31, v17
	s_waitcnt vmcnt(32)
	v_pk_add_f32 v[16:17], v[30:31], v[128:129]
	s_nop 0
	v_cvt_pk_bf16_f32 v5, v16, s0
	v_pk_mul_f32 v[28:29], v[10:11], v[16:17] op_sel:[0,1]
	global_store_short v[148:149], v5, off offset:1536
	v_cvt_pk_bf16_f32 v5, v17, s0
	v_pk_fma_f32 v[30:31], v[6:7], v[16:17], v[28:29] neg_lo:[0,0,1] neg_hi:[0,0,1]
	v_pk_fma_f32 v[16:17], v[6:7], v[16:17], v[28:29] op_sel_hi:[1,0,1]
	global_store_short v[148:149], v5, off offset:1664
	v_mov_b32_e32 v31, v17
	s_waitcnt vmcnt(32)
	v_pk_add_f32 v[16:17], v[30:31], v[130:131]
	s_nop 0
	v_cvt_pk_bf16_f32 v5, v16, s0
	v_pk_mul_f32 v[28:29], v[10:11], v[16:17] op_sel:[0,1]
	global_store_short v[148:149], v5, off offset:2816
	v_cvt_pk_bf16_f32 v5, v17, s0
	v_pk_fma_f32 v[30:31], v[6:7], v[16:17], v[28:29] neg_lo:[0,0,1] neg_hi:[0,0,1]
	v_pk_fma_f32 v[16:17], v[6:7], v[16:17], v[28:29] op_sel_hi:[1,0,1]
	global_store_short v[148:149], v5, off offset:2944
	v_mov_b32_e32 v31, v17
	s_waitcnt vmcnt(32)
	v_pk_add_f32 v[16:17], v[30:31], v[132:133]
	s_nop 0
	v_cvt_pk_bf16_f32 v5, v16, s0
	v_pk_mul_f32 v[28:29], v[10:11], v[16:17] op_sel:[0,1]
	global_store_short v[150:151], v5, off
	v_cvt_pk_bf16_f32 v5, v17, s0
	v_pk_fma_f32 v[30:31], v[6:7], v[16:17], v[28:29] neg_lo:[0,0,1] neg_hi:[0,0,1]
	v_pk_fma_f32 v[16:17], v[6:7], v[16:17], v[28:29] op_sel_hi:[1,0,1]
	global_store_short v[150:151], v5, off offset:128
	v_mov_b32_e32 v31, v17
	s_waitcnt vmcnt(32)
	v_pk_add_f32 v[16:17], v[30:31], v[134:135]
	s_nop 0
	v_cvt_pk_bf16_f32 v5, v16, s0
	v_pk_mul_f32 v[28:29], v[10:11], v[16:17] op_sel:[0,1]
	global_store_short v[150:151], v5, off offset:1280
	v_cvt_pk_bf16_f32 v5, v17, s0
	v_pk_fma_f32 v[30:31], v[6:7], v[16:17], v[28:29] neg_lo:[0,0,1] neg_hi:[0,0,1]
	v_pk_fma_f32 v[16:17], v[6:7], v[16:17], v[28:29] op_sel_hi:[1,0,1]
	global_store_short v[150:151], v5, off offset:1408
	v_mov_b32_e32 v31, v17
	s_waitcnt vmcnt(32)
	v_pk_add_f32 v[16:17], v[30:31], v[136:137]
	s_nop 0
	v_cvt_pk_bf16_f32 v5, v16, s0
	v_pk_mul_f32 v[28:29], v[10:11], v[16:17] op_sel:[0,1]
	global_store_short v[150:151], v5, off offset:2560
	v_cvt_pk_bf16_f32 v5, v17, s0
	v_pk_fma_f32 v[30:31], v[6:7], v[16:17], v[28:29] neg_lo:[0,0,1] neg_hi:[0,0,1]
	v_pk_fma_f32 v[16:17], v[6:7], v[16:17], v[28:29] op_sel_hi:[1,0,1]
	global_store_short v[150:151], v5, off offset:2688
	v_mov_b32_e32 v31, v17
	s_waitcnt vmcnt(32)
	v_pk_add_f32 v[16:17], v[30:31], v[138:139]
	s_nop 0
	v_cvt_pk_bf16_f32 v5, v16, s0
	v_pk_mul_f32 v[28:29], v[10:11], v[16:17] op_sel:[0,1]
	global_store_short v[150:151], v5, off offset:3840
	v_cvt_pk_bf16_f32 v5, v17, s0
	v_pk_fma_f32 v[30:31], v[6:7], v[16:17], v[28:29] neg_lo:[0,0,1] neg_hi:[0,0,1]
	v_pk_fma_f32 v[16:17], v[6:7], v[16:17], v[28:29] op_sel_hi:[1,0,1]
	global_store_short v[150:151], v5, off offset:3968
	v_mov_b32_e32 v31, v17
	s_waitcnt vmcnt(32)
	v_pk_add_f32 v[16:17], v[30:31], v[140:141]
	s_nop 0
	s_cmp_eq_u32 s6, 0
	s_cbranch_scc0 .LBB0_1185
	v_add_u32_e32 v1, s40, v1
	s_movk_i32 s0, 0x3fff
	v_cmp_lt_i32_e32 vcc, s0, v1
	v_readlane_b32 s0, v253, 52
	s_or_b64 s[4:5], vcc, s[4:5]
	s_nop 0
	v_add_u32_e32 v3, s0, v3
	s_andn2_b64 exec, exec, s[4:5]
	s_cbranch_execnz .LBB0_1184
